# attention softmax fast path: exp2 with the carried running max, row sums, one overflow check per tile (falls back to the original max/rescale code, which recomputes the tile); ml_out units remapped so
# speedup vs baseline: 1.0304x; 1.0056x over previous
.LBB0_786:
	s_load_dwordx2 s[4:5], s[0:1], 0x118
	s_waitcnt lgkmcnt(0)
	s_add_i32 s34, s4, s34
	s_cmpk_eq_i32 s4, 0x100
	s_cbranch_scc0 .Lmlo_chk
	s_cmpk_lt_i32 s34, 0x200
	s_cbranch_scc1 .LBB0_787
	s_cmpk_ge_i32 s34, 0x300
	s_cbranch_scc1 .LBB0_924
	s_sub_i32 s34, s34, 0xe0
	s_cmpk_lt_i32 s34, 0x200
	s_cbranch_scc1 .LBB0_924
	s_branch .LBB0_787
.Lmlo_chk:
	s_cmpk_lt_i32 s34, 0x220
	s_cbranch_scc0 .LBB0_924
.LBB0_787:
	s_cmpk_lt_i32 s34, 0x200
	s_cbranch_scc0 .Lmlo_ctx
	s_lshr_b32 s5, s34, 5
	s_mul_i32 s5, s5, 34
	s_and_b32 s4, s34, 31
	s_add_i32 s5, s5, s4
	s_add_i32 s5, s5, 2
	s_branch .Lmlo_go
.Lmlo_ctx:
	s_sub_i32 s4, s34, 0x200
	s_lshr_b32 s5, s4, 1
	s_mul_i32 s5, s5, 34
	s_and_b32 s4, s4, 1
	s_add_i32 s5, s5, s4
.Lmlo_go:
	s_mul_hi_i32 s10, s5, 0x78787879
	s_lshr_b32 s18, s10, 31
	s_ashr_i32 s11, s10, 4
	s_add_i32 s11, s11, s18
	s_mul_i32 s4, s11, 34
	s_sub_i32 s73, s5, s4
	s_cmp_gt_i32 s73, 1
	v_readlane_b32 s36, v254, 23
	s_cselect_b64 s[12:13], -1, 0
	s_cmp_lt_i32 s73, 2
	v_readlane_b32 s37, v254, 24
	s_cselect_b64 s[4:5], -1, 0
	s_or_b64 s[36:37], s[36:37], s[12:13]
	s_andn2_b64 vcc, exec, s[36:37]
	s_cbranch_vccnz .LBB0_786
	s_ashr_i32 s10, s10, 6
	s_add_i32 s10, s10, s18
	s_andn2_b64 vcc, exec, s[4:5]
	s_mov_b64 s[4:5], -1
	s_cbranch_vccnz .LBB0_790
	s_lshl_b32 s4, s10, 8
	s_lshl_b32 s5, s73, 7
	s_add_i32 s4, s4, s5
	s_add_i32 s18, s4, 0x4000
	s_mov_b64 s[4:5], 0

.LBB0_998:
	s_or_b64 exec, exec, s[12:13]
	s_waitcnt vmcnt(0)
	v_mov_b32_e32 v24, v161
	v_mov_b32_e32 v25, v161
	v_mov_b32_e32 v26, v161
	v_mov_b32_e32 v27, v161
	s_lshl_b32 s9, s26, 12
	v_mov_b64_e32 v[30:31], v[26:27]
	v_mov_b64_e32 v[38:39], v[26:27]
	v_mov_b64_e32 v[42:43], v[26:27]
	v_mov_b64_e32 v[46:47], v[26:27]
	v_mov_b64_e32 v[50:51], v[26:27]
	v_mov_b64_e32 v[54:55], v[26:27]
	v_mov_b64_e32 v[58:59], v[26:27]
	v_mov_b64_e32 v[62:63], v[26:27]
	v_mov_b64_e32 v[34:35], v[26:27]
	s_waitcnt vmcnt(0)
	v_mov_b64_e32 v[16:17], v[24:25]
	v_mov_b64_e32 v[20:21], v[24:25]
	v_mov_b64_e32 v[8:9], v[24:25]
	v_mov_b64_e32 v[12:13], v[24:25]
	v_mov_b64_e32 v[0:1], v[24:25]
	v_mov_b64_e32 v[4:5], v[24:25]
	v_ashrrev_i32_e32 v153, 31, v152
	v_ashrrev_i32_e32 v151, 31, v150
	v_mov_b32_e32 v159, v161
	v_mov_b32_e32 v173, v161
	v_mov_b32_e32 v175, v161
	s_add_i32 s13, s9, 0xffffff40
	v_mov_b32_e32 v177, v161
	v_mov_b32_e32 v179, v161
	s_add_i32 s26, s27, 1
	s_add_i32 s27, s8, 64
	s_mov_b32 s29, 0
	v_mov_b32_e32 v154, 0
	v_mov_b32_e32 v203, 0xf149f2ca
	v_mov_b64_e32 v[28:29], v[24:25]
	v_mov_b64_e32 v[36:37], v[24:25]
	v_mov_b64_e32 v[40:41], v[24:25]
	v_mov_b64_e32 v[44:45], v[24:25]
	v_mov_b64_e32 v[48:49], v[24:25]
	v_mov_b64_e32 v[52:53], v[24:25]
	v_mov_b64_e32 v[56:57], v[24:25]
	v_mov_b64_e32 v[60:61], v[24:25]
	v_mov_b32_e32 v162, 0xf149f2ca
	v_mov_b32_e32 v156, 0
	v_mov_b64_e32 v[32:33], v[24:25]
	v_mov_b64_e32 v[18:19], v[26:27]
	v_mov_b64_e32 v[22:23], v[26:27]
	v_mov_b64_e32 v[10:11], v[26:27]
	v_mov_b64_e32 v[14:15], v[26:27]
	v_mov_b64_e32 v[2:3], v[26:27]
	v_mov_b64_e32 v[6:7], v[26:27]
	s_waitcnt lgkmcnt(0)
	s_barrier
	v_mul_f32_e32 v157, 0xbdd53b94, v162
	v_mul_f32_e32 v155, 0xbdd53b94, v203

.LBB0_1003:
	s_or_b64 exec, exec, s[10:11]
	s_bitcmp1_b32 s29, 0
	s_cselect_b32 s8, 0xa800, 0
	v_add_u32_e32 v116, s8, v198
	ds_read_b128 v[116:119], v116
	v_add_u32_e32 v124, s8, v199
	ds_read_b128 v[124:127], v124
	v_add_u32_e32 v128, s8, v200
	ds_read_b128 v[128:131], v128
	v_add_u32_e32 v136, s8, v201
	ds_read_b128 v[136:139], v136
	v_add_u32_e32 v132, s8, v225
	ds_read_b128 v[132:135], v132
	v_add_u32_e32 v140, s8, v226
	ds_read_b128 v[140:143], v140
	s_waitcnt lgkmcnt(5)
	v_mfma_f32_16x16x32_bf16 v[112:115], v[116:119], v[104:107], 0
	v_mfma_f32_16x16x32_bf16 v[120:123], v[116:119], v[108:111], 0
	v_add_u32_e32 v204, s8, v234
	ds_read_b128 v[204:207], v204
	s_waitcnt lgkmcnt(5)
	v_mfma_f32_16x16x32_bf16 v[112:115], v[124:127], v[96:99], v[112:115]
	v_mfma_f32_16x16x32_bf16 v[120:123], v[124:127], v[100:103], v[120:123]
	v_add_u32_e32 v208, s8, v235
	ds_read_b128 v[208:211], v208
	s_waitcnt lgkmcnt(5)
	v_mfma_f32_16x16x32_bf16 v[112:115], v[128:131], v[88:91], v[112:115]
	v_mfma_f32_16x16x32_bf16 v[120:123], v[128:131], v[92:95], v[120:123]
	v_add_u32_e32 v128, s8, v236
	ds_read_b128 v[128:131], v128
	s_waitcnt lgkmcnt(5)
	v_mfma_f32_16x16x32_bf16 v[112:115], v[136:139], v[80:83], v[112:115]
	v_mfma_f32_16x16x32_bf16 v[120:123], v[136:139], v[84:87], v[120:123]
	v_add_u32_e32 v136, s8, v237
	ds_read_b128 v[136:139], v136
	s_waitcnt lgkmcnt(5)
	v_mfma_f32_16x16x32_bf16 v[112:115], v[132:135], v[72:75], v[112:115]
	v_mfma_f32_16x16x32_bf16 v[120:123], v[132:135], v[76:79], v[120:123]
	v_add_u32_e32 v132, s8, v238
	ds_read_b128 v[132:135], v132
	s_waitcnt lgkmcnt(5)
	v_mfma_f32_16x16x32_bf16 v[112:115], v[140:143], v[64:67], v[112:115]
	v_mfma_f32_16x16x32_bf16 v[120:123], v[140:143], v[68:71], v[120:123]
	v_add_u32_e32 v140, s8, v239
	ds_read_b128 v[140:143], v140
	s_waitcnt lgkmcnt(5)
	v_mfma_f32_16x16x32_bf16 v[116:119], v[204:207], v[104:107], 0
	v_mfma_f32_16x16x32_bf16 v[124:127], v[204:207], v[108:111], 0
	v_add_u32_e32 v204, s8, v240
	ds_read_b128 v[204:207], v204
	s_waitcnt lgkmcnt(5)
	v_mfma_f32_16x16x32_bf16 v[116:119], v[208:211], v[96:99], v[116:119]
	v_mfma_f32_16x16x32_bf16 v[124:127], v[208:211], v[100:103], v[124:127]
	v_add_u32_e32 v208, s8, v241
	ds_read_b128 v[208:211], v208
	s_waitcnt lgkmcnt(5)
	v_mfma_f32_16x16x32_bf16 v[116:119], v[128:131], v[88:91], v[116:119]
	v_mfma_f32_16x16x32_bf16 v[124:127], v[128:131], v[92:95], v[124:127]
	s_waitcnt lgkmcnt(4)
	v_mfma_f32_16x16x32_bf16 v[116:119], v[136:139], v[80:83], v[116:119]
	v_mfma_f32_16x16x32_bf16 v[124:127], v[136:139], v[84:87], v[124:127]
	s_waitcnt lgkmcnt(3)
	v_mfma_f32_16x16x32_bf16 v[116:119], v[132:135], v[72:75], v[116:119]
	v_mfma_f32_16x16x32_bf16 v[124:127], v[132:135], v[76:79], v[124:127]
	v_add_u32_e32 v132, s8, v242
	ds_read_b128 v[132:135], v132
	s_waitcnt lgkmcnt(3)
	v_mfma_f32_16x16x32_bf16 v[116:119], v[140:143], v[64:67], v[116:119]
	v_mfma_f32_16x16x32_bf16 v[124:127], v[140:143], v[68:71], v[124:127]
	v_add_u32_e32 v140, s8, v243
	ds_read_b128 v[140:143], v140
	s_waitcnt lgkmcnt(3)
	v_mfma_f32_16x16x32_bf16 v[136:139], v[204:207], v[104:107], 0
	v_mfma_f32_16x16x32_bf16 v[128:131], v[204:207], v[108:111], 0
	v_add_u32_e32 v204, s8, v244
	ds_read_b128 v[204:207], v204
	s_waitcnt lgkmcnt(3)
	v_mfma_f32_16x16x32_bf16 v[136:139], v[208:211], v[96:99], v[136:139]
	v_mfma_f32_16x16x32_bf16 v[128:131], v[208:211], v[100:103], v[128:131]
	v_add_u32_e32 v208, s8, v245
	ds_read_b128 v[208:211], v208
	s_waitcnt lgkmcnt(3)
	v_mfma_f32_16x16x32_bf16 v[136:139], v[132:135], v[88:91], v[136:139]
	v_mfma_f32_16x16x32_bf16 v[128:131], v[132:135], v[92:95], v[128:131]
	s_waitcnt lgkmcnt(2)
	v_mfma_f32_16x16x32_bf16 v[136:139], v[140:143], v[80:83], v[136:139]
	v_mfma_f32_16x16x32_bf16 v[128:131], v[140:143], v[84:87], v[128:131]
	s_waitcnt lgkmcnt(1)
	v_mfma_f32_16x16x32_bf16 v[136:139], v[204:207], v[72:75], v[136:139]
	v_mfma_f32_16x16x32_bf16 v[128:131], v[204:207], v[76:79], v[128:131]
	v_add_u32_e32 v204, s8, v246
	ds_read_b128 v[204:207], v204
	s_waitcnt lgkmcnt(1)
	v_mfma_f32_16x16x32_bf16 v[136:139], v[208:211], v[64:67], v[136:139]
	v_mfma_f32_16x16x32_bf16 v[128:131], v[208:211], v[68:71], v[128:131]
	v_add_u32_e32 v208, s8, v247
	ds_read_b128 v[208:211], v208
	s_waitcnt lgkmcnt(1)
	v_mfma_f32_16x16x32_bf16 v[140:143], v[204:207], v[104:107], 0
	v_mfma_f32_16x16x32_bf16 v[132:135], v[204:207], v[108:111], 0
	v_add_u32_e32 v204, s8, v248
	ds_read_b128 v[204:207], v204
	s_waitcnt lgkmcnt(1)
	v_mfma_f32_16x16x32_bf16 v[140:143], v[208:211], v[96:99], v[140:143]
	v_mfma_f32_16x16x32_bf16 v[132:135], v[208:211], v[100:103], v[132:135]
	v_add_u32_e32 v208, s8, v249
	ds_read_b128 v[208:211], v208
	s_waitcnt lgkmcnt(1)
	v_mfma_f32_16x16x32_bf16 v[140:143], v[204:207], v[88:91], v[140:143]
	v_mfma_f32_16x16x32_bf16 v[132:135], v[204:207], v[92:95], v[132:135]
	v_add_u32_e32 v204, s8, v250
	ds_read_b128 v[204:207], v204
	s_waitcnt lgkmcnt(1)
	v_mfma_f32_16x16x32_bf16 v[140:143], v[208:211], v[80:83], v[140:143]
	v_mfma_f32_16x16x32_bf16 v[132:135], v[208:211], v[84:87], v[132:135]
	v_add_u32_e32 v208, s8, v251
	ds_read_b128 v[208:211], v208
	s_waitcnt lgkmcnt(1)
	v_mfma_f32_16x16x32_bf16 v[140:143], v[204:207], v[72:75], v[140:143]
	v_mfma_f32_16x16x32_bf16 v[132:135], v[204:207], v[76:79], v[132:135]
	s_waitcnt lgkmcnt(0)
	v_mfma_f32_16x16x32_bf16 v[140:143], v[208:211], v[64:67], v[140:143]
	v_mfma_f32_16x16x32_bf16 v[132:135], v[208:211], v[68:71], v[132:135]
	s_nop 7
	v_fmamk_f32 v112, v112, 0x3dd53b94, v157
	v_fmamk_f32 v113, v113, 0x3dd53b94, v157
	v_fmamk_f32 v114, v114, 0x3dd53b94, v157
	v_exp_f32_e32 v112, v112
	v_fmamk_f32 v115, v115, 0x3dd53b94, v157
	v_exp_f32_e32 v113, v113
	v_fmamk_f32 v116, v116, 0x3dd53b94, v157
	v_exp_f32_e32 v114, v114
	v_fmamk_f32 v117, v117, 0x3dd53b94, v157
	v_exp_f32_e32 v115, v115
	v_fmamk_f32 v118, v118, 0x3dd53b94, v157
	v_exp_f32_e32 v116, v116
	v_fmamk_f32 v119, v119, 0x3dd53b94, v157
	v_exp_f32_e32 v117, v117
	v_fmamk_f32 v136, v136, 0x3dd53b94, v157
	v_exp_f32_e32 v118, v118
	v_fmamk_f32 v137, v137, 0x3dd53b94, v157
	v_exp_f32_e32 v119, v119
	v_fmamk_f32 v138, v138, 0x3dd53b94, v157
	v_exp_f32_e32 v136, v136
	v_fmamk_f32 v139, v139, 0x3dd53b94, v157
	v_exp_f32_e32 v137, v137
	v_fmamk_f32 v140, v140, 0x3dd53b94, v157
	v_exp_f32_e32 v138, v138
	v_fmamk_f32 v141, v141, 0x3dd53b94, v157
	v_exp_f32_e32 v139, v139
	v_fmamk_f32 v142, v142, 0x3dd53b94, v157
	v_exp_f32_e32 v140, v140
	v_fmamk_f32 v143, v143, 0x3dd53b94, v157
	v_exp_f32_e32 v141, v141
	v_exp_f32_e32 v142, v142
	v_exp_f32_e32 v143, v143
	s_nop 0
	v_add_f32_e32 v204, v112, v113
	v_add_f32_e32 v205, v114, v115
	v_add_f32_e32 v206, v116, v117
	v_add_f32_e32 v207, v118, v119
	v_add_f32_e32 v208, v136, v137
	v_add_f32_e32 v209, v138, v139
	v_add_f32_e32 v210, v140, v141
	v_add_f32_e32 v211, v142, v143
	v_add_f32_e32 v204, v204, v205
	v_add_f32_e32 v206, v206, v207
	v_add_f32_e32 v208, v208, v209
	v_add_f32_e32 v210, v210, v211
	v_add_f32_e32 v204, v204, v206
	v_add_f32_e32 v208, v208, v210
	v_add_f32_e32 v195, v204, v208
	v_fmamk_f32 v120, v120, 0x3dd53b94, v155
	v_fmamk_f32 v121, v121, 0x3dd53b94, v155
	v_fmamk_f32 v122, v122, 0x3dd53b94, v155
	v_exp_f32_e32 v120, v120
	v_fmamk_f32 v123, v123, 0x3dd53b94, v155
	v_exp_f32_e32 v121, v121
	v_fmamk_f32 v124, v124, 0x3dd53b94, v155
	v_exp_f32_e32 v122, v122
	v_fmamk_f32 v125, v125, 0x3dd53b94, v155
	v_exp_f32_e32 v123, v123
	v_fmamk_f32 v126, v126, 0x3dd53b94, v155
	v_exp_f32_e32 v124, v124
	v_fmamk_f32 v127, v127, 0x3dd53b94, v155
	v_exp_f32_e32 v125, v125
	v_fmamk_f32 v128, v128, 0x3dd53b94, v155
	v_exp_f32_e32 v126, v126
	v_fmamk_f32 v129, v129, 0x3dd53b94, v155
	v_exp_f32_e32 v127, v127
	v_fmamk_f32 v130, v130, 0x3dd53b94, v155
	v_exp_f32_e32 v128, v128
	v_fmamk_f32 v131, v131, 0x3dd53b94, v155
	v_exp_f32_e32 v129, v129
	v_fmamk_f32 v132, v132, 0x3dd53b94, v155
	v_exp_f32_e32 v130, v130
	v_fmamk_f32 v133, v133, 0x3dd53b94, v155
	v_exp_f32_e32 v131, v131
	v_fmamk_f32 v134, v134, 0x3dd53b94, v155
	v_exp_f32_e32 v132, v132
	v_fmamk_f32 v135, v135, 0x3dd53b94, v155
	v_exp_f32_e32 v133, v133
	v_exp_f32_e32 v134, v134
	v_exp_f32_e32 v135, v135
	s_nop 0
	v_add_f32_e32 v204, v120, v121
	v_add_f32_e32 v205, v122, v123
	v_add_f32_e32 v206, v124, v125
	v_add_f32_e32 v207, v126, v127
	v_add_f32_e32 v208, v128, v129
	v_add_f32_e32 v209, v130, v131
	v_add_f32_e32 v210, v132, v133
	v_add_f32_e32 v211, v134, v135
	v_add_f32_e32 v204, v204, v205
	v_add_f32_e32 v206, v206, v207
	v_add_f32_e32 v208, v208, v209
	v_add_f32_e32 v210, v210, v211
	v_add_f32_e32 v204, v204, v206
	v_add_f32_e32 v208, v208, v210
	v_add_f32_e32 v230, v204, v208
	v_add_f32_e32 v211, v195, v230
	v_cmp_ge_f32_e32 vcc, 0x47800000, v211
	s_cmp_eq_u64 vcc, exec
	s_cbranch_scc0 .Lattn_slow
	v_add_f32_e32 v156, v156, v195
	v_add_f32_e32 v154, v154, v230
	v_cvt_pk_bf16_f32 v119, v118, v119
	v_cvt_pk_bf16_f32 v118, v116, v117
	v_cvt_pk_bf16_f32 v116, v112, v113
	v_cvt_pk_bf16_f32 v117, v114, v115
	v_cvt_pk_bf16_f32 v112, v136, v137
	v_cvt_pk_bf16_f32 v113, v138, v139
	v_cvt_pk_bf16_f32 v114, v140, v141
	v_cvt_pk_bf16_f32 v115, v142, v143
	v_cvt_pk_bf16_f32 v127, v126, v127
	v_cvt_pk_bf16_f32 v126, v124, v125
	v_cvt_pk_bf16_f32 v124, v120, v121
	v_cvt_pk_bf16_f32 v125, v122, v123
	v_cvt_pk_bf16_f32 v120, v128, v129
	v_cvt_pk_bf16_f32 v121, v130, v131
	v_cvt_pk_bf16_f32 v122, v132, v133
	v_cvt_pk_bf16_f32 v123, v134, v135
.Lattn_pv:
	v_add3_u32 v230, s8, v144, v202
	ds_read_b64 v[128:129], v230 offset:24576
	ds_read_b64 v[130:131], v230 offset:24608
	ds_read_b64 v[132:133], v230 offset:24640
	ds_read_b64 v[134:135], v230 offset:24672
	ds_read_b64 v[136:137], v230 offset:26880
	ds_read_b64 v[138:139], v230 offset:26912
	ds_read_b64 v[140:141], v230 offset:26944
	ds_read_b64 v[142:143], v230 offset:26976
	ds_read_b64 v[204:205], v230 offset:29184
	ds_read_b64 v[206:207], v230 offset:29216
	ds_read_b64 v[208:209], v230 offset:29248
	ds_read_b64 v[210:211], v230 offset:29280
	s_waitcnt lgkmcnt(10)
	v_mfma_f32_16x16x32_bf16 v[60:63], v[128:131], v[116:119], v[60:63]
	v_mfma_f32_16x16x32_bf16 v[56:59], v[128:131], v[124:127], v[56:59]
	ds_read_b64 v[128:129], v230 offset:31488
	ds_read_b64 v[130:131], v230 offset:31520
	s_waitcnt lgkmcnt(10)
	v_mfma_f32_16x16x32_bf16 v[60:63], v[132:135], v[112:115], v[60:63]
	v_mfma_f32_16x16x32_bf16 v[56:59], v[132:135], v[120:123], v[56:59]
	ds_read_b64 v[132:133], v230 offset:31552
	ds_read_b64 v[134:135], v230 offset:31584
	s_waitcnt lgkmcnt(10)
	v_mfma_f32_16x16x32_bf16 v[52:55], v[136:139], v[116:119], v[52:55]
	v_mfma_f32_16x16x32_bf16 v[48:51], v[136:139], v[124:127], v[48:51]
	ds_read_b64 v[136:137], v230 offset:33792
	ds_read_b64 v[138:139], v230 offset:33824
	s_waitcnt lgkmcnt(10)
	v_mfma_f32_16x16x32_bf16 v[52:55], v[140:143], v[112:115], v[52:55]
	v_mfma_f32_16x16x32_bf16 v[48:51], v[140:143], v[120:123], v[48:51]
	ds_read_b64 v[140:141], v230 offset:33856
	ds_read_b64 v[142:143], v230 offset:33888
	s_waitcnt lgkmcnt(10)
	v_mfma_f32_16x16x32_bf16 v[44:47], v[204:207], v[116:119], v[44:47]
	v_mfma_f32_16x16x32_bf16 v[40:43], v[204:207], v[124:127], v[40:43]
	ds_read_b64 v[204:205], v230 offset:36096
	ds_read_b64 v[206:207], v230 offset:36128
	s_waitcnt lgkmcnt(10)
	v_mfma_f32_16x16x32_bf16 v[44:47], v[208:211], v[112:115], v[44:47]
	v_mfma_f32_16x16x32_bf16 v[40:43], v[208:211], v[120:123], v[40:43]
	ds_read_b64 v[208:209], v230 offset:36160
	ds_read_b64 v[210:211], v230 offset:36192
	s_waitcnt lgkmcnt(10)
	v_mfma_f32_16x16x32_bf16 v[36:39], v[128:131], v[116:119], v[36:39]
	v_mfma_f32_16x16x32_bf16 v[28:31], v[128:131], v[124:127], v[28:31]
	ds_read_b64 v[128:129], v230 offset:38400
	ds_read_b64 v[130:131], v230 offset:38432
	s_waitcnt lgkmcnt(10)
	v_mfma_f32_16x16x32_bf16 v[36:39], v[132:135], v[112:115], v[36:39]
	v_mfma_f32_16x16x32_bf16 v[28:31], v[132:135], v[120:123], v[28:31]
	ds_read_b64 v[132:133], v230 offset:38464
	ds_read_b64 v[134:135], v230 offset:38496
	s_waitcnt lgkmcnt(10)
	v_mfma_f32_16x16x32_bf16 v[24:27], v[136:139], v[116:119], v[24:27]
	v_mfma_f32_16x16x32_bf16 v[32:35], v[136:139], v[124:127], v[32:35]
	ds_read_b64 v[136:137], v230 offset:40704
	ds_read_b64 v[138:139], v230 offset:40736
	s_waitcnt lgkmcnt(10)
	v_mfma_f32_16x16x32_bf16 v[24:27], v[140:143], v[112:115], v[24:27]
	v_mfma_f32_16x16x32_bf16 v[32:35], v[140:143], v[120:123], v[32:35]
	ds_read_b64 v[140:141], v230 offset:40768
	ds_read_b64 v[142:143], v230 offset:40800
	s_waitcnt lgkmcnt(10)
	v_mfma_f32_16x16x32_bf16 v[16:19], v[204:207], v[116:119], v[16:19]
	v_mfma_f32_16x16x32_bf16 v[20:23], v[204:207], v[124:127], v[20:23]
	s_waitcnt lgkmcnt(8)
	v_mfma_f32_16x16x32_bf16 v[16:19], v[208:211], v[112:115], v[16:19]
	v_mfma_f32_16x16x32_bf16 v[20:23], v[208:211], v[120:123], v[20:23]
	s_waitcnt lgkmcnt(6)
	v_mfma_f32_16x16x32_bf16 v[8:11], v[128:131], v[116:119], v[8:11]
	v_mfma_f32_16x16x32_bf16 v[12:15], v[128:131], v[124:127], v[12:15]
	s_waitcnt lgkmcnt(4)
	v_mfma_f32_16x16x32_bf16 v[8:11], v[132:135], v[112:115], v[8:11]
	v_mfma_f32_16x16x32_bf16 v[12:15], v[132:135], v[120:123], v[12:15]
	s_waitcnt lgkmcnt(2)
	v_mfma_f32_16x16x32_bf16 v[0:3], v[136:139], v[116:119], v[0:3]
	v_mfma_f32_16x16x32_bf16 v[4:7], v[136:139], v[124:127], v[4:7]
	s_waitcnt lgkmcnt(0)
	v_mfma_f32_16x16x32_bf16 v[0:3], v[140:143], v[112:115], v[0:3]
	v_mfma_f32_16x16x32_bf16 v[4:7], v[140:143], v[120:123], v[4:7]
	s_add_i32 s13, s13, 64
	s_add_i32 s27, s27, 64
	s_cmp_eq_u32 s26, s28
	s_waitcnt vmcnt(0) lgkmcnt(0)
	s_barrier
	s_cbranch_scc1 .LBB0_1011
	s_mov_b32 s29, s28
	s_branch .LBB0_999
.Lattn_slow:
	v_add_u32_e32 v116, s8, v198
	ds_read_b128 v[116:119], v116
	v_add_u32_e32 v124, s8, v199
	ds_read_b128 v[124:127], v124
	v_add_u32_e32 v128, s8, v200
	ds_read_b128 v[128:131], v128
	v_add_u32_e32 v136, s8, v201
	ds_read_b128 v[136:139], v136
	v_add_u32_e32 v132, s8, v225
	ds_read_b128 v[132:135], v132
	v_add_u32_e32 v140, s8, v226
	ds_read_b128 v[140:143], v140
	s_waitcnt lgkmcnt(5)
	v_mfma_f32_16x16x32_bf16 v[112:115], v[116:119], v[104:107], 0
	v_mfma_f32_16x16x32_bf16 v[120:123], v[116:119], v[108:111], 0
	v_add_u32_e32 v204, s8, v234
	ds_read_b128 v[204:207], v204
	s_waitcnt lgkmcnt(5)
	v_mfma_f32_16x16x32_bf16 v[112:115], v[124:127], v[96:99], v[112:115]
	v_mfma_f32_16x16x32_bf16 v[120:123], v[124:127], v[100:103], v[120:123]
	v_add_u32_e32 v208, s8, v235
	ds_read_b128 v[208:211], v208
	s_waitcnt lgkmcnt(5)
	v_mfma_f32_16x16x32_bf16 v[112:115], v[128:131], v[88:91], v[112:115]
	v_mfma_f32_16x16x32_bf16 v[120:123], v[128:131], v[92:95], v[120:123]
	v_add_u32_e32 v128, s8, v236
	ds_read_b128 v[128:131], v128
	s_waitcnt lgkmcnt(5)
	v_mfma_f32_16x16x32_bf16 v[112:115], v[136:139], v[80:83], v[112:115]
	v_mfma_f32_16x16x32_bf16 v[120:123], v[136:139], v[84:87], v[120:123]
	v_add_u32_e32 v136, s8, v237
	ds_read_b128 v[136:139], v136
	s_waitcnt lgkmcnt(5)
	v_mfma_f32_16x16x32_bf16 v[112:115], v[132:135], v[72:75], v[112:115]
	v_mfma_f32_16x16x32_bf16 v[120:123], v[132:135], v[76:79], v[120:123]
	v_add_u32_e32 v132, s8, v238
	ds_read_b128 v[132:135], v132
	s_waitcnt lgkmcnt(5)
	v_mfma_f32_16x16x32_bf16 v[112:115], v[140:143], v[64:67], v[112:115]
	v_mfma_f32_16x16x32_bf16 v[120:123], v[140:143], v[68:71], v[120:123]
	v_add_u32_e32 v140, s8, v239
	ds_read_b128 v[140:143], v140
	s_waitcnt lgkmcnt(5)
	v_mfma_f32_16x16x32_bf16 v[116:119], v[204:207], v[104:107], 0
	v_mfma_f32_16x16x32_bf16 v[124:127], v[204:207], v[108:111], 0
	v_add_u32_e32 v204, s8, v240
	ds_read_b128 v[204:207], v204
	s_waitcnt lgkmcnt(5)
	v_mfma_f32_16x16x32_bf16 v[116:119], v[208:211], v[96:99], v[116:119]
	v_mfma_f32_16x16x32_bf16 v[124:127], v[208:211], v[100:103], v[124:127]
	v_add_u32_e32 v208, s8, v241
	ds_read_b128 v[208:211], v208
	s_waitcnt lgkmcnt(5)
	v_mfma_f32_16x16x32_bf16 v[116:119], v[128:131], v[88:91], v[116:119]
	v_mfma_f32_16x16x32_bf16 v[124:127], v[128:131], v[92:95], v[124:127]
	s_waitcnt lgkmcnt(4)
	v_mfma_f32_16x16x32_bf16 v[116:119], v[136:139], v[80:83], v[116:119]
	v_mfma_f32_16x16x32_bf16 v[124:127], v[136:139], v[84:87], v[124:127]
	s_waitcnt lgkmcnt(3)
	v_mfma_f32_16x16x32_bf16 v[116:119], v[132:135], v[72:75], v[116:119]
	v_mfma_f32_16x16x32_bf16 v[124:127], v[132:135], v[76:79], v[124:127]
	v_add_u32_e32 v132, s8, v242
	ds_read_b128 v[132:135], v132
	s_waitcnt lgkmcnt(3)
	v_mfma_f32_16x16x32_bf16 v[116:119], v[140:143], v[64:67], v[116:119]
	v_mfma_f32_16x16x32_bf16 v[124:127], v[140:143], v[68:71], v[124:127]
	v_add_u32_e32 v140, s8, v243
	ds_read_b128 v[140:143], v140
	s_waitcnt lgkmcnt(3)
	v_mfma_f32_16x16x32_bf16 v[136:139], v[204:207], v[104:107], 0
	v_mfma_f32_16x16x32_bf16 v[128:131], v[204:207], v[108:111], 0
	v_add_u32_e32 v204, s8, v244
	ds_read_b128 v[204:207], v204
	s_waitcnt lgkmcnt(3)
	v_mfma_f32_16x16x32_bf16 v[136:139], v[208:211], v[96:99], v[136:139]
	v_mfma_f32_16x16x32_bf16 v[128:131], v[208:211], v[100:103], v[128:131]
	v_add_u32_e32 v208, s8, v245
	ds_read_b128 v[208:211], v208
	s_waitcnt lgkmcnt(3)
	v_mfma_f32_16x16x32_bf16 v[136:139], v[132:135], v[88:91], v[136:139]
	v_mfma_f32_16x16x32_bf16 v[128:131], v[132:135], v[92:95], v[128:131]
	s_waitcnt lgkmcnt(2)
	v_mfma_f32_16x16x32_bf16 v[136:139], v[140:143], v[80:83], v[136:139]
	v_mfma_f32_16x16x32_bf16 v[128:131], v[140:143], v[84:87], v[128:131]
	s_waitcnt lgkmcnt(1)
	v_mfma_f32_16x16x32_bf16 v[136:139], v[204:207], v[72:75], v[136:139]
	v_mfma_f32_16x16x32_bf16 v[128:131], v[204:207], v[76:79], v[128:131]
	v_add_u32_e32 v204, s8, v246
	ds_read_b128 v[204:207], v204
	s_waitcnt lgkmcnt(1)
	v_mfma_f32_16x16x32_bf16 v[136:139], v[208:211], v[64:67], v[136:139]
	v_mfma_f32_16x16x32_bf16 v[128:131], v[208:211], v[68:71], v[128:131]
	v_add_u32_e32 v208, s8, v247
	ds_read_b128 v[208:211], v208
	s_waitcnt lgkmcnt(1)
	v_mfma_f32_16x16x32_bf16 v[140:143], v[204:207], v[104:107], 0
	v_mfma_f32_16x16x32_bf16 v[132:135], v[204:207], v[108:111], 0
	v_add_u32_e32 v204, s8, v248
	ds_read_b128 v[204:207], v204
	s_waitcnt lgkmcnt(1)
	v_mfma_f32_16x16x32_bf16 v[140:143], v[208:211], v[96:99], v[140:143]
	v_mfma_f32_16x16x32_bf16 v[132:135], v[208:211], v[100:103], v[132:135]
	v_add_u32_e32 v208, s8, v249
	ds_read_b128 v[208:211], v208
	s_waitcnt lgkmcnt(1)
	v_mfma_f32_16x16x32_bf16 v[140:143], v[204:207], v[88:91], v[140:143]
	v_mfma_f32_16x16x32_bf16 v[132:135], v[204:207], v[92:95], v[132:135]
	v_add_u32_e32 v204, s8, v250
	ds_read_b128 v[204:207], v204
	s_waitcnt lgkmcnt(1)
	v_mfma_f32_16x16x32_bf16 v[140:143], v[208:211], v[80:83], v[140:143]
	v_mfma_f32_16x16x32_bf16 v[132:135], v[208:211], v[84:87], v[132:135]
	v_add_u32_e32 v208, s8, v251
	ds_read_b128 v[208:211], v208
	s_waitcnt lgkmcnt(1)
	v_mfma_f32_16x16x32_bf16 v[140:143], v[204:207], v[72:75], v[140:143]
	v_mfma_f32_16x16x32_bf16 v[132:135], v[204:207], v[76:79], v[132:135]
	s_waitcnt lgkmcnt(0)
	v_mfma_f32_16x16x32_bf16 v[140:143], v[208:211], v[64:67], v[140:143]
	v_mfma_f32_16x16x32_bf16 v[132:135], v[208:211], v[68:71], v[132:135]
	s_nop 7
	v_max_f32_e32 v157, v112, v112
	v_max_f32_e32 v195, v114, v114
	v_max_f32_e32 v155, v113, v113
	v_max_f32_e32 v155, v157, v155
	v_max_f32_e32 v157, v115, v115
	v_max_f32_e32 v157, v195, v157
	v_max_f32_e32 v195, v119, v119
	v_max_f32_e32 v204, v118, v118
	v_max_f32_e32 v195, v204, v195
	v_max3_f32 v195, v116, v117, v195
	v_max3_f32 v155, v155, v157, v195
	v_max_f32_e32 v157, v139, v139
	v_max_f32_e32 v195, v138, v138
	v_max_f32_e32 v157, v195, v157
	v_max_f32_e32 v195, v143, v143
	v_max_f32_e32 v204, v142, v142
	v_max_f32_e32 v195, v204, v195
	v_max3_f32 v157, v136, v137, v157
	v_max3_f32 v195, v140, v141, v195
	v_max3_f32 v155, v155, v157, v195
	v_sub_f32_e32 v157, v155, v162
	v_cmp_ge_f32_e32 vcc, s89, v157
	s_cmp_eq_u64 vcc, exec
	s_cbranch_scc1 .LBB0_1005
	v_and_b32_e32 v195, 64, v227
	v_xor_b32_e32 v157, 16, v227
	v_add_u32_e32 v195, 64, v195
	v_cmp_lt_i32_e32 vcc, v157, v195
	s_nop 1
	v_cndmask_b32_e32 v157, v227, v157, vcc
	v_lshlrev_b32_e32 v157, 2, v157
	ds_bpermute_b32 v157, v157, v155
	v_max_f32_e32 v155, v155, v155
	s_waitcnt lgkmcnt(0)
	v_max_f32_e32 v157, v157, v157
	v_max_f32_e32 v155, v155, v157
	v_xor_b32_e32 v157, 32, v227
	v_cmp_lt_i32_e32 vcc, v157, v195
	s_nop 1
	v_cndmask_b32_e32 v157, v227, v157, vcc
	v_lshlrev_b32_e32 v157, 2, v157
	ds_bpermute_b32 v157, v157, v155
	s_waitcnt lgkmcnt(0)
	v_max3_f32 v155, v162, v155, v157
	v_sub_f32_e32 v157, v162, v155
	v_mul_f32_e32 v157, 0x3dd53b94, v157
	v_exp_f32_e32 v162, v157
	s_nop 0
	v_mul_f32_e32 v156, v156, v162
	v_pk_mul_f32 v[62:63], v[62:63], v[162:163] op_sel_hi:[1,0]
	v_pk_mul_f32 v[60:61], v[60:61], v[162:163] op_sel_hi:[1,0]
	v_pk_mul_f32 v[54:55], v[54:55], v[162:163] op_sel_hi:[1,0]
	v_pk_mul_f32 v[52:53], v[52:53], v[162:163] op_sel_hi:[1,0]
	v_pk_mul_f32 v[46:47], v[46:47], v[162:163] op_sel_hi:[1,0]
	v_pk_mul_f32 v[44:45], v[44:45], v[162:163] op_sel_hi:[1,0]
	v_pk_mul_f32 v[38:39], v[38:39], v[162:163] op_sel_hi:[1,0]
	v_pk_mul_f32 v[36:37], v[36:37], v[162:163] op_sel_hi:[1,0]
	v_pk_mul_f32 v[26:27], v[26:27], v[162:163] op_sel_hi:[1,0]
	v_pk_mul_f32 v[24:25], v[24:25], v[162:163] op_sel_hi:[1,0]
	v_pk_mul_f32 v[18:19], v[18:19], v[162:163] op_sel_hi:[1,0]
	v_pk_mul_f32 v[16:17], v[16:17], v[162:163] op_sel_hi:[1,0]
	v_pk_mul_f32 v[10:11], v[10:11], v[162:163] op_sel_hi:[1,0]
	v_pk_mul_f32 v[8:9], v[8:9], v[162:163] op_sel_hi:[1,0]
	v_pk_mul_f32 v[2:3], v[2:3], v[162:163] op_sel_hi:[1,0]
	v_pk_mul_f32 v[0:1], v[0:1], v[162:163] op_sel_hi:[1,0]
	v_mov_b32_e32 v162, v155

.LBB0_1007:
	v_add_f32_e32 v155, 0, v155
	v_add_f32_e32 v155, v204, v155
	v_add_f32_e32 v155, v205, v155
	v_add_f32_e32 v155, v206, v155
	v_add_f32_e32 v155, v207, v155
	v_add_f32_e32 v155, v208, v155
	v_add_f32_e32 v155, v230, v155
	v_add_f32_e32 v155, v195, v155
	v_add_f32_e32 v136, v136, v155
	v_add_f32_e32 v136, v137, v136
	v_add_f32_e32 v136, v138, v136
	v_mul_f32_e32 v155, 0xbdd53b94, v203
	v_add_f32_e32 v136, v139, v136
	v_fmamk_f32 v120, v120, 0x3dd53b94, v155
	v_add_f32_e32 v136, v140, v136
	v_exp_f32_e32 v120, v120
	v_fmamk_f32 v121, v121, 0x3dd53b94, v155
	v_add_f32_e32 v136, v141, v136
	v_exp_f32_e32 v121, v121
	v_fmamk_f32 v122, v122, 0x3dd53b94, v155
	v_add_f32_e32 v136, v142, v136
	v_exp_f32_e32 v122, v122
	v_fmamk_f32 v123, v123, 0x3dd53b94, v155
	v_add_f32_e32 v136, v143, v136
	v_exp_f32_e32 v123, v123
	v_fmamk_f32 v124, v124, 0x3dd53b94, v155
	v_add_f32_e32 v156, v156, v136
	v_add_f32_e32 v136, 0, v120
	v_exp_f32_e32 v137, v124
	v_add_f32_e32 v136, v121, v136
	v_add_f32_e32 v136, v122, v136
	v_add_f32_e32 v136, v123, v136
	v_fmamk_f32 v125, v125, 0x3dd53b94, v155
	v_add_f32_e32 v124, v137, v136
	v_exp_f32_e32 v136, v125
	v_fmamk_f32 v125, v126, 0x3dd53b94, v155
	v_exp_f32_e32 v138, v125
	v_fmamk_f32 v125, v127, 0x3dd53b94, v155
	v_exp_f32_e32 v127, v125
	v_fmamk_f32 v125, v128, 0x3dd53b94, v155
	v_exp_f32_e32 v128, v125
	v_fmamk_f32 v125, v129, 0x3dd53b94, v155
	v_add_f32_e32 v124, v136, v124
	v_exp_f32_e32 v129, v125
	v_fmamk_f32 v125, v130, 0x3dd53b94, v155
	v_add_f32_e32 v124, v138, v124
	v_exp_f32_e32 v130, v125
	v_fmamk_f32 v125, v131, 0x3dd53b94, v155
	v_add_f32_e32 v124, v127, v124
	v_exp_f32_e32 v131, v125
	v_fmamk_f32 v125, v132, 0x3dd53b94, v155
	v_add_f32_e32 v124, v128, v124
	v_exp_f32_e32 v132, v125
	v_fmamk_f32 v125, v133, 0x3dd53b94, v155
	v_add_f32_e32 v124, v129, v124
	v_exp_f32_e32 v133, v125
	v_fmamk_f32 v125, v134, 0x3dd53b94, v155
	v_add_f32_e32 v124, v130, v124
	v_exp_f32_e32 v134, v125
	v_fmamk_f32 v125, v135, 0x3dd53b94, v155
	v_add_f32_e32 v124, v131, v124
	v_exp_f32_e32 v135, v125
	v_add_f32_e32 v124, v132, v124
	v_add_f32_e32 v124, v133, v124
	v_add_f32_e32 v124, v134, v124
	v_add_f32_e32 v124, v135, v124
	v_add_f32_e32 v154, v154, v124
	v_cvt_pk_bf16_f32 v124, v120, v121
	v_cvt_pk_bf16_f32 v125, v122, v123
	v_cvt_pk_bf16_f32 v126, v137, v136
	v_cvt_pk_bf16_f32 v127, v138, v127
	v_cvt_pk_bf16_f32 v120, v128, v129
	v_cvt_pk_bf16_f32 v121, v130, v131
	v_cvt_pk_bf16_f32 v122, v132, v133
	v_cvt_pk_bf16_f32 v123, v134, v135
	s_branch .Lattn_pv
